# grid barriers 1-7 replaced by a hand-written variant: XCD arrive, XCD-last writeback + top arrive, global-last bumps one flag per workgroup, each workgroup polls only its own flag; on top of v64
# baseline (speedup 1.0000x reference)
.LBB0_123:
	s_waitcnt vmcnt(0)
	s_barrier
	s_mov_b64 s[0:1], exec
	v_readlane_b32 s2, v252, 1
	v_readlane_b32 s3, v252, 2
	s_and_b64 s[2:3], s[0:1], s[2:3]
	s_mov_b64 exec, s[2:3]
	s_cbranch_execz .LBB0_176
	s_add_u32 s98, s58, 0xc000
	s_addc_u32 s99, s59, 0
	s_waitcnt vmcnt(0) lgkmcnt(0)
	v_mov_b32_e32 v253, 0x26f00
	ds_read2_b32 v[254:255], v253 offset1:1
	v_readlane_b32 s100, v252, 5
	s_lshl_b32 s100, s100, 8
	s_add_u32 s100, s100, 0xc00
	v_mov_b32_e32 v253, s100
	s_waitcnt lgkmcnt(0)
	v_readfirstlane_b32 s100, v254
	v_readfirstlane_b32 s101, v255
	v_mov_b32_e32 v254, 1
	global_atomic_add v255, v253, v254, s[98:99] sc0
	s_mul_i32 s100, s100, 1
	s_mul_i32 s101, s101, 1
	s_waitcnt vmcnt(0)
	v_add_u32_e32 v255, 1, v255
	v_cmp_eq_u32_e32 vcc, s100, v255
	s_cbranch_vccz .Lpb1_notlast
	buffer_wbl2 sc1
	s_waitcnt vmcnt(0)
	v_mov_b32_e32 v253, 0x300
	global_atomic_add v255, v253, v254, s[98:99] sc0
	s_waitcnt vmcnt(0)
	v_add_u32_e32 v255, 1, v255
	v_cmp_eq_u32_e32 vcc, s101, v255
	s_cbranch_vccz .Lpb1_notlast
	v_readlane_b32 s100, v252, 26
	s_mov_b64 exec, -1
	v_mbcnt_lo_u32_b32 v253, -1, 0
	v_mbcnt_hi_u32_b32 v253, -1, v253
	v_mov_b32_e32 v254, 1
	s_mov_b32 s101, 0
.Lpb1_flags:
	v_add_u32_e32 v255, s101, v253
	v_cmp_gt_u32_e32 vcc, s100, v255
	v_lshlrev_b32_e32 v255, 3, v255
	v_add_u32_e32 v255, 0x1c00, v255
	s_mov_b64 exec, vcc
	global_atomic_add v255, v254, s[98:99]
	s_mov_b64 exec, -1
	s_add_u32 s101, s101, 64
	s_cmp_lt_u32 s101, s100
	s_cbranch_scc1 .Lpb1_flags
	s_mov_b64 exec, 1
.Lpb1_notlast:
	v_readlane_b32 s101, v252, 0
	s_lshl_b32 s101, s101, 3
	s_add_u32 s101, s101, 0x1c00
	v_mov_b32_e32 v253, s101
	s_mov_b32 s100, 0
.Lpb1_poll:
	global_load_dword v255, v253, s[98:99] sc1
	s_waitcnt vmcnt(0)
	v_cmp_le_u32_e32 vcc, 1, v255
	s_add_u32 s100, s100, 1
	s_cbranch_vccnz .Lpb1_done
	s_cmp_lt_u32 s100, 4096
	s_cbranch_scc0 .Lpb1_done
	s_sleep 1
	s_branch .Lpb1_poll
.Lpb1_done:
	buffer_inv sc1
	s_waitcnt vmcnt(0)
	s_branch .Lpadskip_4
	s_nop 0
	s_nop 0
	s_nop 0
	s_nop 0
	s_nop 0
	s_nop 0
	s_nop 0
	s_nop 0
	s_nop 0
	s_nop 0
	s_nop 0
	s_nop 0
	s_nop 0
	s_nop 0
	s_nop 0
	s_nop 0
	s_nop 0
	s_nop 0
	s_nop 0
	s_nop 0
	s_nop 0
	s_nop 0
.Lpadskip_4:
.LBB0_176:
	s_or_b64 exec, exec, s[0:1]
	s_add_u32 s52, s58, 0x2400000
	s_addc_u32 s53, s59, 0
	v_mov_b32_e32 v8, v182
	v_readlane_b32 s0, v252, 0
	s_waitcnt lgkmcnt(0)
	s_barrier
	s_cmpk_gt_u32 s0, 0x8ff
	v_readfirstlane_b32 s0, v8
	s_cbranch_scc1 .LBB0_192
	v_ashrrev_i32_e32 v1, 31, v8
	v_lshrrev_b32_e32 v1, 26, v1
	v_add_u32_e32 v1, v8, v1
	v_ashrrev_i32_e32 v9, 6, v1
	v_bfe_i32 v1, v8, 27, 1
	v_lshlrev_b32_e32 v0, 4, v8
	v_lshrrev_b32_e32 v1, 22, v1
	v_add_u32_e32 v1, v0, v1
	v_and_b32_e32 v1, 0xfffffc00, v1
	v_sub_u32_e32 v1, v0, v1
	v_lshrrev_b32_e32 v2, 4, v1
	v_bitop3_b32 v2, v2, v1, 32 bitop3:0x6c
	v_ashrrev_i32_e32 v1, 31, v1
	v_lshrrev_b32_e32 v1, 26, v1
	v_add_u32_e32 v1, v2, v1
	v_ashrrev_i32_e32 v10, 6, v1
	v_mul_i32_i24_e32 v4, 64, v10
	v_sub_u32_e32 v2, v2, v4
	v_mov_b32_e32 v4, 1
	v_lshlrev_b32_e32 v3, 3, v9
	v_lshlrev_b32_e32 v1, 5, v9
	v_ashrrev_i16_sdwa v2, v4, sext(v2) dst_sel:DWORD dst_unused:UNUSED_PAD src0_sel:DWORD src1_sel:BYTE_0
	v_and_b32_e32 v3, 0xffff0, v3
	v_and_b32_e32 v1, 32, v1
	v_bfe_i32 v11, v2, 0, 16
	v_add_u32_e32 v1, v1, v11
	v_add_lshl_u32 v2, v10, v3, 12
	v_add_u32_e32 v0, 0x2000, v0
	v_lshl_add_u32 v128, v1, 1, v2
	v_ashrrev_i32_e32 v1, 31, v0
	v_readlane_b32 s3, v252, 0
	v_lshrrev_b32_e32 v1, 22, v1
	s_and_b32 s2, s3, 7
	v_add_u32_e32 v1, v0, v1
	s_lshr_b32 s3, s3, 3
	s_mulk_i32 s2, 0x120
	v_ashrrev_i32_e32 v12, 10, v1
	s_add_i32 s2, s2, s3
	v_mul_i32_i24_e32 v1, 0x400, v12
	s_mul_i32 s3, s2, 0xe38f
	v_sub_u32_e32 v0, v0, v1
	s_lshr_b32 s3, s3, 24
	v_lshrrev_b32_e32 v1, 4, v0
	s_lshl_b32 s4, s3, 3
	s_mulk_i32 s3, 0x120
	v_bitop3_b32 v0, v1, v0, 32 bitop3:0x6c
	s_sub_i32 s2, s2, s3
	v_ashrrev_i32_e32 v2, 31, v0
	s_and_b32 s3, s2, 7
	v_lshrrev_b32_e32 v2, 26, v2
	s_ashr_i32 s6, s0, 6
	s_or_b32 s33, s3, s4
	s_bfe_u32 s36, s2, 0xd0003
	v_add_u32_e32 v2, v0, v2
	s_ashr_i32 s1, s0, 8
	v_ashrrev_i32_e32 v13, 6, v2
	v_and_b32_e32 v2, 0xc0, v2
	s_lshl_b32 s2, s6, 10
	s_lshl_b32 s7, s33, 20
	s_lshl_b32 s3, s36, 20
	v_sub_u32_e32 v0, v0, v2
	s_add_u32 s20, s52, s3
	v_lshlrev_b32_e32 v1, 3, v12
	v_lshlrev_b32_e32 v3, 5, v12
	v_ashrrev_i16_sdwa v0, v4, sext(v0) dst_sel:DWORD dst_unused:UNUSED_PAD src0_sel:DWORD src1_sel:BYTE_0
	s_addc_u32 s21, s53, 0
	s_add_i32 s3, s2, 0
	v_and_b32_e32 v1, 0xffff0, v1
	v_and_b32_e32 v3, 32, v3
	v_bfe_i32 v14, v0, 0, 16
	s_add_i32 m0, s3, 0x10000
	v_add_u32_e32 v0, v3, v14
	v_add_lshl_u32 v1, v13, v1, 12
	global_load_lds_dwordx4 v128, s[20:21]
	s_add_i32 m0, s3, 0x12000
	v_lshl_add_u32 v130, v0, 1, v1
	s_add_u32 s4, s20, 0x80000
	global_load_lds_dwordx4 v130, s[20:21]
	s_addc_u32 s5, s21, 0
	s_add_i32 m0, s3, 0x14000
	v_mov_b32_e32 v133, 0
	global_load_lds_dwordx4 v128, s[4:5]
	s_add_i32 m0, s3, 0x16000
	v_mov_b32_e32 v129, v133
	global_load_lds_dwordx4 v130, s[4:5]
	v_readlane_b32 s4, v252, 6
	v_readlane_b32 s5, v252, 7
	s_add_u32 s18, s4, s7
	s_addc_u32 s19, s5, 0
	s_add_i32 s24, s3, 0x2000
	s_mov_b32 m0, s3
	s_add_u32 s4, s18, 0x80000
	global_load_lds_dwordx4 v128, s[18:19]
	s_mov_b32 m0, s24
	s_addc_u32 s5, s19, 0
	s_add_i32 s25, s3, 0x4000
	global_load_lds_dwordx4 v130, s[18:19]
	s_mov_b32 m0, s25
	s_add_i32 s26, s3, 0x6000
	global_load_lds_dwordx4 v128, s[4:5]
	s_mov_b32 m0, s26
	v_mov_b32_e32 v131, v133
	global_load_lds_dwordx4 v130, s[4:5]
	s_cmp_eq_u32 s1, 1
	v_lshl_add_u64 v[6:7], s[20:21], 0, v[128:129]
	v_lshl_add_u64 v[4:5], s[20:21], 0, v[130:131]
	v_lshl_add_u64 v[0:1], s[18:19], 0, v[128:129]
	s_cselect_b64 s[4:5], -1, 0
	s_cmp_lg_u32 s1, 1
	v_lshl_add_u64 v[2:3], s[18:19], 0, v[130:131]
	s_cbranch_scc1 .LBB0_179
	s_barrier

.LBB0_192:
	s_waitcnt vmcnt(0)
	s_waitcnt vmcnt(0)
	s_barrier
	s_mov_b64 s[0:1], exec
	v_readlane_b32 s2, v252, 1
	v_readlane_b32 s3, v252, 2
	s_and_b64 s[2:3], s[0:1], s[2:3]
	s_mov_b64 exec, s[2:3]
	s_cbranch_execz .LBB0_244
	s_add_u32 s98, s58, 0xc000
	s_addc_u32 s99, s59, 0
	s_waitcnt vmcnt(0) lgkmcnt(0)
	v_mov_b32_e32 v253, 0x26f00
	ds_read2_b32 v[254:255], v253 offset1:1
	v_readlane_b32 s100, v252, 5
	s_lshl_b32 s100, s100, 8
	s_add_u32 s100, s100, 0xc00
	v_mov_b32_e32 v253, s100
	s_waitcnt lgkmcnt(0)
	v_readfirstlane_b32 s100, v254
	v_readfirstlane_b32 s101, v255
	v_mov_b32_e32 v254, 1
	global_atomic_add v255, v253, v254, s[98:99] sc0
	s_mul_i32 s100, s100, 2
	s_mul_i32 s101, s101, 2
	s_waitcnt vmcnt(0)
	v_add_u32_e32 v255, 1, v255
	v_cmp_eq_u32_e32 vcc, s100, v255
	s_cbranch_vccz .Lpb2_notlast
	buffer_wbl2 sc1
	s_waitcnt vmcnt(0)
	v_mov_b32_e32 v253, 0x300
	global_atomic_add v255, v253, v254, s[98:99] sc0
	s_waitcnt vmcnt(0)
	v_add_u32_e32 v255, 1, v255
	v_cmp_eq_u32_e32 vcc, s101, v255
	s_cbranch_vccz .Lpb2_notlast
	v_readlane_b32 s100, v252, 26
	s_mov_b64 exec, -1
	v_mbcnt_lo_u32_b32 v253, -1, 0
	v_mbcnt_hi_u32_b32 v253, -1, v253
	v_mov_b32_e32 v254, 1
	s_mov_b32 s101, 0

.Lpb2_poll:
	global_load_dword v255, v253, s[98:99] sc1
	s_waitcnt vmcnt(0)
	v_cmp_le_u32_e32 vcc, 2, v255
	s_add_u32 s100, s100, 1
	s_cbranch_vccnz .Lpb2_done
	s_cmp_lt_u32 s100, 4096
	s_cbranch_scc0 .Lpb2_done
	s_sleep 1
	s_branch .Lpb2_poll

.Lpadskip_5:
.LBB0_244:
	v_writelane_b32 v252, s52, 27
	s_nop 1
	v_writelane_b32 v252, s53, 28
	s_or_b64 exec, exec, s[0:1]
	v_readlane_b32 s1, v252, 0
	s_and_b32 s0, s1, 8
	s_cmp_eq_u32 s0, 0
	s_cselect_b64 s[2:3], -1, 0
	s_cmp_lg_u32 s0, 0
	s_cselect_b64 s[4:5], -1, 0
	v_writelane_b32 v252, s4, 29
	s_cmpk_gt_i32 s1, 0x2ff
	s_cselect_b64 s[0:1], -1, 0
	v_writelane_b32 v252, s5, 30
	v_writelane_b32 v252, s2, 31
	s_or_b64 s[0:1], s[0:1], s[2:3]
	s_and_b64 vcc, exec, s[0:1]
	v_mbcnt_lo_u32_b32 v180, -1, 0
	s_waitcnt lgkmcnt(0)
	s_barrier
	v_writelane_b32 v252, s3, 32
	s_cbranch_vccnz .LBB0_259
	s_add_u32 s75, s58, 0xe800000
	s_addc_u32 s0, s59, 0
	v_writelane_b32 v252, s0, 33
	s_add_u32 s0, s58, 0x100000
	v_writelane_b32 v252, s0, 34
	s_addc_u32 s0, s59, 0
	v_writelane_b32 v252, s0, 35
	s_add_i32 s0, 0, 0x19800
	v_writelane_b32 v252, s0, 37
	v_mov_b32_e32 v73, 0
	s_movk_i32 s42, 0x1800
	s_movk_i32 s43, 0x1000
	s_add_i32 s39, 0, 0x11000
	s_add_i32 s94, 0, 0x8800
	v_mov_b32_e32 v80, 0x42800000
	v_mbcnt_hi_u32_b32 v81, -1, v180
	v_mov_b32_e32 v82, 0xff800000
	v_readlane_b32 s51, v252, 0
	s_mov_b32 s74, 0xff800000
	s_branch .LBB0_247

.LBB0_419:
	s_waitcnt vmcnt(0)
	s_waitcnt vmcnt(0) lgkmcnt(0)
	s_barrier
	s_mov_b64 s[4:5], exec
	v_readlane_b32 s0, v252, 1
	v_readlane_b32 s1, v252, 2
	v_readlane_b32 s42, v252, 27
	s_and_b64 s[0:1], s[4:5], s[0:1]
	v_readlane_b32 s43, v252, 28
	s_mov_b64 exec, s[0:1]
	s_cbranch_execz .LBB0_471
	s_add_u32 s98, s58, 0xc000
	s_addc_u32 s99, s59, 0
	s_waitcnt vmcnt(0) lgkmcnt(0)
	v_mov_b32_e32 v253, 0x26f00
	ds_read2_b32 v[254:255], v253 offset1:1
	v_readlane_b32 s100, v252, 5
	s_lshl_b32 s100, s100, 8
	s_add_u32 s100, s100, 0xc00
	v_mov_b32_e32 v253, s100
	s_waitcnt lgkmcnt(0)
	v_readfirstlane_b32 s100, v254
	v_readfirstlane_b32 s101, v255
	v_mov_b32_e32 v254, 1
	global_atomic_add v255, v253, v254, s[98:99] sc0
	s_mul_i32 s100, s100, 3
	s_mul_i32 s101, s101, 3
	s_waitcnt vmcnt(0)
	v_add_u32_e32 v255, 1, v255
	v_cmp_eq_u32_e32 vcc, s100, v255
	s_cbranch_vccz .Lpb3_notlast
	buffer_wbl2 sc1
	s_waitcnt vmcnt(0)
	v_mov_b32_e32 v253, 0x300
	global_atomic_add v255, v253, v254, s[98:99] sc0
	s_waitcnt vmcnt(0)
	v_add_u32_e32 v255, 1, v255
	v_cmp_eq_u32_e32 vcc, s101, v255
	s_cbranch_vccz .Lpb3_notlast
	v_readlane_b32 s100, v252, 26
	s_mov_b64 exec, -1
	v_mbcnt_lo_u32_b32 v253, -1, 0
	v_mbcnt_hi_u32_b32 v253, -1, v253
	v_mov_b32_e32 v254, 1
	s_mov_b32 s101, 0

.Lpb3_poll:
	global_load_dword v255, v253, s[98:99] sc1
	s_waitcnt vmcnt(0)
	v_cmp_le_u32_e32 vcc, 3, v255
	s_add_u32 s100, s100, 1
	s_cbranch_vccnz .Lpb3_done
	s_cmp_lt_u32 s100, 4096
	s_cbranch_scc0 .Lpb3_done
	s_sleep 1
	s_branch .Lpb3_poll
.Lpb3_done:
	buffer_inv sc1
	s_waitcnt vmcnt(0)
	s_branch .Lpadskip_6
	s_nop 0
	s_nop 0
	s_nop 0
	s_nop 0
	s_nop 0
	s_nop 0
	s_nop 0
	s_nop 0
	s_nop 0
	s_nop 0
	s_nop 0
	s_nop 0
	s_nop 0
	s_nop 0
	s_nop 0
	s_nop 0
	s_nop 0
	s_nop 0
	s_nop 0
	s_nop 0
	s_nop 0
	s_nop 0
	s_nop 0
	s_nop 0
	s_nop 0
	s_nop 0
	s_nop 0
	s_nop 0
	s_nop 0
	s_nop 0
	s_nop 0
	s_nop 0
	s_nop 0
	s_nop 0
	s_nop 0
	s_nop 0
	s_nop 0
	s_nop 0
	s_nop 0
	s_nop 0
	s_nop 0
	s_nop 0
	s_nop 0
	s_nop 0
	s_nop 0
	s_nop 0
	s_nop 0
	s_nop 0
	s_nop 0
	s_nop 0
.Lpadskip_6:
.LBB0_471:
	s_or_b64 exec, exec, s[4:5]
	v_readlane_b32 s0, v252, 0
	s_lshl_b32 s67, s0, 9
	s_waitcnt lgkmcnt(0)
	v_mov_b32_e32 v0, v182
	s_barrier
	s_lshl_b32 s66, s96, 9
	s_mov_b32 s6, s67

.Ld3_done:
.LBB0_543:
	s_waitcnt vmcnt(0)
	s_barrier
	s_mov_b64 s[4:5], exec
	v_readlane_b32 s0, v252, 1
	v_readlane_b32 s1, v252, 2
	s_and_b64 s[0:1], s[4:5], s[0:1]
	s_mov_b64 exec, s[0:1]
	s_cbranch_execz .LBB0_595
	s_add_u32 s98, s58, 0xc000
	s_addc_u32 s99, s59, 0
	s_waitcnt vmcnt(0) lgkmcnt(0)
	v_mov_b32_e32 v253, 0x26f00
	ds_read2_b32 v[254:255], v253 offset1:1
	v_readlane_b32 s100, v252, 5
	s_lshl_b32 s100, s100, 8
	s_add_u32 s100, s100, 0xc00
	v_mov_b32_e32 v253, s100
	s_waitcnt lgkmcnt(0)
	v_readfirstlane_b32 s100, v254
	v_readfirstlane_b32 s101, v255
	v_mov_b32_e32 v254, 1
	global_atomic_add v255, v253, v254, s[98:99] sc0
	s_mul_i32 s100, s100, 4
	s_mul_i32 s101, s101, 4
	s_waitcnt vmcnt(0)
	v_add_u32_e32 v255, 1, v255
	v_cmp_eq_u32_e32 vcc, s100, v255
	s_cbranch_vccz .Lpb4_notlast
	buffer_wbl2 sc1
	s_waitcnt vmcnt(0)
	v_mov_b32_e32 v253, 0x300
	global_atomic_add v255, v253, v254, s[98:99] sc0
	s_waitcnt vmcnt(0)
	v_add_u32_e32 v255, 1, v255
	v_cmp_eq_u32_e32 vcc, s101, v255
	s_cbranch_vccz .Lpb4_notlast
	v_readlane_b32 s100, v252, 26
	s_mov_b64 exec, -1
	v_mbcnt_lo_u32_b32 v253, -1, 0
	v_mbcnt_hi_u32_b32 v253, -1, v253
	v_mov_b32_e32 v254, 1
	s_mov_b32 s101, 0

.Lpb4_poll:
	global_load_dword v255, v253, s[98:99] sc1
	s_waitcnt vmcnt(0)
	v_cmp_le_u32_e32 vcc, 4, v255
	s_add_u32 s100, s100, 1
	s_cbranch_vccnz .Lpb4_done
	s_cmp_lt_u32 s100, 4096
	s_cbranch_scc0 .Lpb4_done
	s_sleep 1
	s_branch .Lpb4_poll
.Lpb4_done:
	buffer_inv sc1
	s_waitcnt vmcnt(0)
	s_branch .Lpadskip_7
	s_nop 0
	s_nop 0
	s_nop 0
	s_nop 0
	s_nop 0
	s_nop 0
	s_nop 0
	s_nop 0
	s_nop 0
	s_nop 0
	s_nop 0
	s_nop 0
	s_nop 0
	s_nop 0
	s_nop 0
	s_nop 0
	s_nop 0
	s_nop 0
	s_nop 0
	s_nop 0
	s_nop 0
	s_nop 0
	s_nop 0
	s_nop 0
	s_nop 0
	s_nop 0
	s_nop 0
	s_nop 0
	s_nop 0
	s_nop 0
	s_nop 0
	s_nop 0
	s_nop 0
	s_nop 0
	s_nop 0
	s_nop 0
	s_nop 0
	s_nop 0
	s_nop 0
	s_nop 0
	s_nop 0
	s_nop 0
	s_nop 0
	s_nop 0
	s_nop 0
	s_nop 0
	s_nop 0
	s_nop 0
	s_nop 0
	s_nop 0
	s_nop 0
	s_nop 0
	s_nop 0
	s_nop 0
.Lpadskip_7:
.LBB0_595:
	s_or_b64 exec, exec, s[4:5]
	v_readlane_b32 s0, v252, 29
	v_readlane_b32 s1, v252, 30
	s_andn2_b64 vcc, exec, s[0:1]
	s_waitcnt lgkmcnt(0)
	s_barrier
	s_cbranch_vccnz .LBB0_612
	v_mov_b32_e32 v0, v182
	s_mov_b32 s2, 0x200000
	v_add_u32_e32 v66, s67, v0
	v_cmp_gt_i32_e32 vcc, s2, v66
	s_and_saveexec_b64 s[8:9], vcc
	s_cbranch_execz .LBB0_611
	s_add_u32 s10, s58, 0x100000
	s_addc_u32 s11, s59, 0
	s_add_u32 s12, s58, 0x8800000
	s_addc_u32 s13, s59, 0
	s_add_u32 s14, s58, 0x16800000
	s_addc_u32 s15, s59, 0
	v_lshlrev_b32_e32 v0, 3, v0
	v_readlane_b32 s3, v252, 0
	v_mov_b32_e32 v65, 0
	s_add_i32 s25, s66, s66
	s_lshl_b32 s0, s96, 10
	s_mul_i32 s1, s96, 0x600
	v_lshl_add_u32 v80, s3, 12, v0
	s_lshl_b32 s3, s96, 14
	s_mov_b64 s[16:17], 0
	s_mov_b64 s[18:19], 0x4000
	s_mov_b64 s[20:21], 0x8000
	s_movk_i32 s24, 0x1800
	s_add_i32 s25, s25, s66
	s_mov_b32 s26, 0x1fffff
	v_mov_b32_e32 v24, v65
	v_mov_b32_e32 v25, v65
	v_mov_b32_e32 v26, v65
	v_mov_b32_e32 v27, v65
	v_mov_b32_e32 v28, v65
	v_mov_b32_e32 v29, v65
	v_mov_b32_e32 v30, v65
	v_mov_b32_e32 v31, v65
	v_mov_b32_e32 v32, v65
	v_mov_b32_e32 v33, v65
	v_mov_b32_e32 v34, v65
	v_mov_b32_e32 v35, v65
	v_mov_b32_e32 v36, v65
	v_mov_b32_e32 v37, v65
	v_mov_b32_e32 v38, v65
	v_mov_b32_e32 v39, v65
	v_mov_b32_e32 v40, v65
	v_mov_b32_e32 v41, v65
	v_mov_b32_e32 v42, v65
	v_mov_b32_e32 v43, v65
	v_mov_b32_e32 v44, v65
	v_mov_b32_e32 v45, v65
	v_mov_b32_e32 v46, v65
	v_mov_b32_e32 v47, v65
	s_branch .LBB0_599

.LBB0_677:
	s_or_b64 exec, exec, s[0:1]
	v_add_u32_e32 v46, 0xc0, v152
	s_waitcnt lgkmcnt(1)
	ds_read2st64_b32 v[44:45], v46 offset0:2 offset1:6
	s_waitcnt lgkmcnt(1)
	ds_read2st64_b32 v[46:47], v46 offset0:10 offset1:14
	ds_read_b32 v48, v174 offset:704
	ds_read_b32 v49, v175 offset:704
	ds_read_b32 v50, v176 offset:704
	s_waitcnt lgkmcnt(4)
	v_add_f32_e32 v44, v44, v45
	s_waitcnt lgkmcnt(3)
	v_add_f32_e32 v44, v44, v46
	v_add_f32_e32 v44, v44, v47
	s_waitcnt lgkmcnt(1)
	v_fmac_f32_e32 v44, v48, v49
	s_waitcnt lgkmcnt(0)
	v_max_f32_e32 v45, v50, v50
	v_max_f32_e64 v44, |v44|, v45
	v_rcp_f32_e32 v44, v44
	v_and_b32_e32 v50, 0xffff0000, v86
	v_mul_f32_e32 v50, 0xbfb8aa3b, v50
	v_exp_f32_e32 v51, v50
	v_pk_mul_f32 v[42:43], v[42:43], v[44:45] op_sel_hi:[1,0]
	v_pk_mul_f32 v[40:41], v[40:41], v[44:45] op_sel_hi:[1,0]
	v_pk_mul_f32 v[46:47], v[2:3], v[44:45] op_sel_hi:[1,0]
	v_pk_mul_f32 v[48:49], v[0:1], v[44:45] op_sel_hi:[1,0]
	v_lshlrev_b32_e32 v45, 16, v86
	v_mul_f32_e32 v45, 0xbfb8aa3b, v45
	v_exp_f32_e32 v45, v45
	v_lshlrev_b32_e32 v2, 16, v84
	v_and_b32_e32 v3, 0xffff0000, v84
	v_mul_f32_e32 v2, 0xbfb8aa3b, v2
	v_add_f32_e32 v45, 1.0, v45
	v_rcp_f32_e32 v50, v45
	v_add_f32_e32 v45, 1.0, v51
	v_lshlrev_b32_e32 v51, 16, v87
	v_mul_f32_e32 v51, 0xbfb8aa3b, v51
	v_exp_f32_e32 v52, v51
	v_and_b32_e32 v51, 0xffff0000, v87
	v_mul_f32_e32 v51, 0xbfb8aa3b, v51
	v_mul_f32_e32 v3, 0xbfb8aa3b, v3
	v_exp_f32_e32 v53, v51
	v_exp_f32_e32 v2, v2
	v_exp_f32_e32 v3, v3
	v_rcp_f32_e32 v51, v45
	v_add_f32_e32 v45, 1.0, v52
	v_rcp_f32_e32 v52, v45
	v_add_f32_e32 v45, 1.0, v53
	v_add_f32_e32 v0, 1.0, v2
	v_add_f32_e32 v1, 1.0, v3
	v_lshlrev_b32_e32 v2, 16, v85
	v_and_b32_e32 v3, 0xffff0000, v85
	v_rcp_f32_e32 v53, v45
	v_pk_mul_f32 v[84:85], v[50:51], v[48:49]
	v_pk_mul_f32 v[38:39], v[38:39], v[44:45] op_sel_hi:[1,0]
	v_pk_mul_f32 v[36:37], v[36:37], v[44:45] op_sel_hi:[1,0]
	v_pk_mul_f32 v[34:35], v[34:35], v[44:45] op_sel_hi:[1,0]
	v_lshlrev_b32_e32 v45, 16, v80
	v_and_b32_e32 v50, 0xffff0000, v80
	v_mul_f32_e32 v45, 0xbfb8aa3b, v45
	v_mul_f32_e32 v50, 0xbfb8aa3b, v50
	v_exp_f32_e32 v45, v45
	v_exp_f32_e32 v50, v50
	v_mul_f32_e32 v2, 0xbfb8aa3b, v2
	v_mul_f32_e32 v3, 0xbfb8aa3b, v3
	v_pk_mul_f32 v[76:77], v[52:53], v[46:47]
	v_pk_mul_f32 v[32:33], v[32:33], v[44:45] op_sel_hi:[1,0]
	v_add_f32_e32 v44, 1.0, v45
	v_add_f32_e32 v45, 1.0, v50
	v_lshlrev_b32_e32 v50, 16, v81
	v_and_b32_e32 v51, 0xffff0000, v81
	v_lshlrev_b32_e32 v52, 16, v82
	v_and_b32_e32 v53, 0xffff0000, v82
	v_exp_f32_e32 v2, v2
	v_exp_f32_e32 v3, v3
	v_mul_f32_e32 v50, 0xbfb8aa3b, v50
	v_mul_f32_e32 v51, 0xbfb8aa3b, v51
	v_mul_f32_e32 v52, 0xbfb8aa3b, v52
	v_mul_f32_e32 v53, 0xbfb8aa3b, v53
	v_exp_f32_e32 v50, v50
	v_exp_f32_e32 v51, v51
	v_exp_f32_e32 v52, v52
	v_exp_f32_e32 v53, v53
	v_lshlrev_b32_e32 v54, 16, v83
	v_and_b32_e32 v55, 0xffff0000, v83
	v_rcp_f32_e32 v0, v0
	v_rcp_f32_e32 v1, v1
	v_add_f32_e32 v2, 1.0, v2
	v_add_f32_e32 v3, 1.0, v3
	v_mul_f32_e32 v54, 0xbfb8aa3b, v54
	v_mul_f32_e32 v55, 0xbfb8aa3b, v55
	v_rcp_f32_e32 v2, v2
	v_rcp_f32_e32 v3, v3
	v_rcp_f32_e32 v44, v44
	v_rcp_f32_e32 v45, v45
	v_add_f32_e32 v50, 1.0, v50
	v_add_f32_e32 v51, 1.0, v51
	v_add_f32_e32 v52, 1.0, v52
	v_add_f32_e32 v53, 1.0, v53
	v_exp_f32_e32 v54, v54
	v_exp_f32_e32 v55, v55
	v_rcp_f32_e32 v50, v50
	v_rcp_f32_e32 v51, v51
	v_rcp_f32_e32 v52, v52
	v_rcp_f32_e32 v53, v53
	v_pk_mul_f32 v[0:1], v[0:1], v[40:41]
	v_pk_mul_f32 v[2:3], v[2:3], v[42:43]
	v_add_f32_e32 v40, v0, v1
	v_add_f32_e32 v54, 1.0, v54
	v_add_f32_e32 v55, 1.0, v55
	v_pk_mul_f32 v[82:83], v[44:45], v[36:37]
	v_add_f32_e32 v40, v2, v40
	v_rcp_f32_e32 v54, v54
	v_rcp_f32_e32 v55, v55
	v_pk_mul_f32 v[80:81], v[50:51], v[38:39]
	v_pk_mul_f32 v[74:75], v[52:53], v[32:33]
	v_add_f32_e32 v32, v82, v83
	v_add_f32_e32 v40, v3, v40
	v_add_f32_e32 v32, v80, v32
	v_add_f32_e32 v40, v84, v40
	v_add_f32_e32 v32, v81, v32
	v_add_f32_e32 v40, v85, v40
	v_add_f32_e32 v32, v74, v32
	v_add_f32_e32 v40, v76, v40
	v_pk_mul_f32 v[72:73], v[54:55], v[34:35]
	v_add_f32_e32 v32, v75, v32
	v_add_f32_e32 v40, v77, v40
	v_add_f32_e32 v32, v72, v32
	v_add_f32_e32 v56, 0, v40
	v_add_f32_e32 v32, v73, v32
	v_pk_mul_f32 v[40:41], v[0:1], v[0:1]
	v_add_f32_e32 v44, v32, v56
	v_pk_mul_f32 v[32:33], v[82:83], v[82:83]
	v_pk_mul_f32 v[42:43], v[2:3], v[2:3]
	v_pk_mul_f32 v[34:35], v[80:81], v[80:81]
	v_add_f32_e32 v32, v32, v33
	v_add_f32_e32 v33, v40, v41
	v_add_f32_e32 v32, v34, v32
	v_add_f32_e32 v33, v42, v33
	v_pk_mul_f32 v[46:47], v[84:85], v[84:85]
	v_pk_mul_f32 v[36:37], v[74:75], v[74:75]
	v_add_f32_e32 v32, v35, v32
	v_add_f32_e32 v33, v43, v33
	v_add_f32_e32 v32, v36, v32
	v_add_f32_e32 v33, v46, v33
	v_pk_mul_f32 v[48:49], v[76:77], v[76:77]
	v_pk_mul_f32 v[38:39], v[72:73], v[72:73]
	v_add_f32_e32 v32, v37, v32
	v_add_f32_e32 v33, v47, v33
	v_add_f32_e32 v32, v38, v32
	v_add_f32_e32 v33, v48, v33
	v_add_f32_e32 v32, v39, v32
	v_add_f32_e32 v33, v49, v33
	v_add_f32_e32 v35, v33, v32
	v_mov_b32_e32 v34, v44
	s_nop 1
	v_permlane16_swap_b32 v44, v34
	v_mov_b32_e32 v36, v35
	s_nop 1
	v_permlane16_swap_b32 v35, v36
	s_lshl_b64 s[0:1], s[20:21], 10
	s_waitcnt lgkmcnt(1)
	v_add_f32_e32 v32, v44, v34
	s_waitcnt lgkmcnt(0)
	v_add_f32_e32 v34, v35, v36
	v_mov_b32_e32 v33, v32
	s_nop 1
	v_permlane32_swap_b32 v32, v33
	v_mov_b32_e32 v35, v34
	s_nop 1
	v_permlane32_swap_b32 v34, v35
	s_and_saveexec_b64 s[20:21], vcc
	s_cbranch_execz .LBB0_614
	s_waitcnt lgkmcnt(1)
	v_add_f32_e32 v32, v32, v33
	s_waitcnt lgkmcnt(0)
	v_add_f32_e32 v33, v34, v35
	v_add_u32_e32 v34, 0xc0, v177
	ds_write2st64_b32 v34, v32, v33 offset0:2 offset1:18
	s_branch .LBB0_614
	s_nop 0
	s_nop 0
	s_nop 0
	s_nop 0
	s_nop 0
	s_nop 0
	s_nop 0
	s_nop 0
	s_nop 0
	s_nop 0
	s_nop 0
	s_nop 0
	s_nop 0
	s_nop 0
	s_nop 0
	s_nop 0
	s_nop 0
	s_nop 0
	s_nop 0
	s_nop 0
	s_nop 0
	s_nop 0
	s_nop 0
	s_nop 0
	s_nop 0
	s_nop 0
	s_nop 0
	s_nop 0
	s_nop 0
	s_nop 0
	s_nop 0
	s_nop 0
	s_nop 0
	s_nop 0
	s_nop 0
	s_nop 0
	s_nop 0
	s_nop 0
	s_nop 0
	s_nop 0
	s_nop 0
	s_nop 0
	s_nop 0
	s_nop 0
	s_nop 0
	s_nop 0
	s_nop 0
	s_nop 0
	s_nop 0
	s_nop 0
	s_nop 0
	s_nop 0
	s_nop 0
	s_nop 0

.LBB0_696:
	s_waitcnt vmcnt(0)
	s_waitcnt lgkmcnt(0)
	s_barrier
	s_mov_b64 s[0:1], exec
	v_readlane_b32 s2, v252, 1
	v_readlane_b32 s3, v252, 2
	s_and_b64 s[2:3], s[0:1], s[2:3]
	s_mov_b64 exec, s[2:3]
	s_cbranch_execz .LBB0_748
	s_add_u32 s98, s58, 0xc000
	s_addc_u32 s99, s59, 0
	s_waitcnt vmcnt(0) lgkmcnt(0)
	v_mov_b32_e32 v253, 0x26f00
	ds_read2_b32 v[254:255], v253 offset1:1
	v_readlane_b32 s100, v252, 5
	s_lshl_b32 s100, s100, 8
	s_add_u32 s100, s100, 0xc00
	v_mov_b32_e32 v253, s100
	s_waitcnt lgkmcnt(0)
	v_readfirstlane_b32 s100, v254
	v_readfirstlane_b32 s101, v255
	v_mov_b32_e32 v254, 1
	global_atomic_add v255, v253, v254, s[98:99] sc0
	s_mul_i32 s100, s100, 5
	s_mul_i32 s101, s101, 5
	s_waitcnt vmcnt(0)
	v_add_u32_e32 v255, 1, v255
	v_cmp_eq_u32_e32 vcc, s100, v255
	s_cbranch_vccz .Lpb5_notlast
	buffer_wbl2 sc1
	s_waitcnt vmcnt(0)
	v_mov_b32_e32 v253, 0x300
	global_atomic_add v255, v253, v254, s[98:99] sc0
	s_waitcnt vmcnt(0)
	v_add_u32_e32 v255, 1, v255
	v_cmp_eq_u32_e32 vcc, s101, v255
	s_cbranch_vccz .Lpb5_notlast
	v_readlane_b32 s100, v252, 26
	s_mov_b64 exec, -1
	v_mbcnt_lo_u32_b32 v253, -1, 0
	v_mbcnt_hi_u32_b32 v253, -1, v253
	v_mov_b32_e32 v254, 1
	s_mov_b32 s101, 0

.Lpb5_poll:
	global_load_dword v255, v253, s[98:99] sc1
	s_waitcnt vmcnt(0)
	v_cmp_le_u32_e32 vcc, 5, v255
	s_add_u32 s100, s100, 1
	s_cbranch_vccnz .Lpb5_done
	s_cmp_lt_u32 s100, 4096
	s_cbranch_scc0 .Lpb5_done
	s_sleep 1
	s_branch .Lpb5_poll

.Lpadskip_8:
.LBB0_748:
	s_or_b64 exec, exec, s[0:1]
	s_add_u32 s6, s58, 0x16800000
	s_addc_u32 s7, s59, 0
	s_add_u32 s8, s58, 0x1a800000
	s_addc_u32 s9, s59, 0
	v_readlane_b32 s2, v252, 0
	s_cmpk_lt_u32 s2, 0x200
	s_cselect_b64 s[42:43], -1, 0
	s_lshl_b32 s0, s2, 3
	s_and_b32 s0, s0, 56
	s_bfe_u32 s1, s2, 0x30003
	v_mov_b32_e32 v9, v182
	s_or_b32 s62, s1, s0
	s_lshr_b32 s63, s2, 6
	s_waitcnt lgkmcnt(0)
	s_barrier
	s_cmpk_gt_u32 s2, 0x1ff
	v_readfirstlane_b32 s2, v9
	s_cbranch_scc1 .LBB0_780
	v_ashrrev_i32_e32 v1, 31, v9
	v_lshrrev_b32_e32 v1, 26, v1
	v_add_u32_e32 v1, v9, v1
	v_ashrrev_i32_e32 v10, 6, v1
	v_bfe_i32 v1, v9, 27, 1
	v_lshlrev_b32_e32 v0, 4, v9
	v_lshrrev_b32_e32 v1, 22, v1
	v_add_u32_e32 v1, v0, v1
	v_and_b32_e32 v1, 0xfffffc00, v1
	v_sub_u32_e32 v1, v0, v1
	v_lshrrev_b32_e32 v2, 4, v1
	v_bitop3_b32 v2, v2, v1, 32 bitop3:0x6c
	v_ashrrev_i32_e32 v1, 31, v1
	v_lshrrev_b32_e32 v1, 26, v1
	v_lshlrev_b32_e32 v3, 3, v10
	v_add_u32_e32 v1, v2, v1
	v_and_b32_e32 v3, -16, v3
	v_ashrrev_i32_e32 v8, 6, v1
	v_add_u32_e32 v16, v8, v3
	v_mul_i32_i24_e32 v3, 64, v8
	v_lshlrev_b32_e32 v1, 5, v10
	v_sub_u32_e32 v2, v2, v3
	v_mov_b32_e32 v11, 1
	v_and_b32_e32 v1, 32, v1
	v_ashrrev_i16_sdwa v14, v11, sext(v2) dst_sel:DWORD dst_unused:UNUSED_PAD src0_sel:DWORD src1_sel:BYTE_0
	v_add_u32_sdwa v1, v1, sext(v14) dst_sel:DWORD dst_unused:UNUSED_PAD src0_sel:DWORD src1_sel:WORD_0
	v_lshlrev_b32_e32 v2, 12, v16
	v_add_u32_e32 v0, 0x2000, v0
	v_lshl_add_u32 v132, v1, 1, v2
	v_ashrrev_i32_e32 v1, 31, v0
	v_lshrrev_b32_e32 v1, 22, v1
	v_add_u32_e32 v1, v0, v1
	v_ashrrev_i32_e32 v13, 10, v1
	v_mul_i32_i24_e32 v1, 0x400, v13
	v_sub_u32_e32 v0, v0, v1
	v_writelane_b32 v252, s42, 27
	s_add_u32 s40, s58, 0x1400000
	v_lshrrev_b32_e32 v1, 4, v0
	v_writelane_b32 v252, s43, 28
	s_addc_u32 s41, s59, 0
	s_ashr_i32 s4, s2, 6
	v_bitop3_b32 v0, v1, v0, 32 bitop3:0x6c
	s_ashr_i32 s3, s2, 8
	v_ashrrev_i32_e32 v2, 31, v0
	s_lshl_b32 s44, s4, 10
	s_lshl_b32 s12, s62, 20
	v_readlane_b32 s0, v252, 6
	v_lshrrev_b32_e32 v2, 26, v2
	v_readlane_b32 s1, v252, 7
	s_add_u32 s10, s0, s12
	v_lshlrev_b32_e32 v1, 3, v13
	v_add_u32_e32 v2, v0, v2
	s_addc_u32 s11, s1, 0
	s_lshl_b32 s36, s63, 20
	v_and_b32_e32 v1, -16, v1
	v_ashrrev_i32_e32 v12, 6, v2
	v_and_b32_e32 v2, 0xc0, v2
	s_add_u32 s0, s40, s36
	v_add_u32_e32 v17, v12, v1
	v_lshlrev_b32_e32 v1, 5, v13
	v_sub_u32_e32 v0, v0, v2
	s_addc_u32 s1, s41, 0
	s_add_i32 s45, s44, 0
	v_and_b32_e32 v1, 32, v1
	v_ashrrev_i16_sdwa v15, v11, sext(v0) dst_sel:DWORD dst_unused:UNUSED_PAD src0_sel:DWORD src1_sel:BYTE_0
	s_add_i32 m0, s45, 0x10000
	v_add_u32_sdwa v0, v1, sext(v15) dst_sel:DWORD dst_unused:UNUSED_PAD src0_sel:DWORD src1_sel:WORD_0
	v_lshlrev_b32_e32 v1, 12, v17
	global_load_lds_dwordx4 v132, s[0:1]
	s_add_i32 m0, s45, 0x12000
	v_lshl_add_u32 v134, v0, 1, v1
	s_add_u32 s14, s0, 0x80000
	global_load_lds_dwordx4 v134, s[0:1]
	s_addc_u32 s15, s1, 0
	s_add_i32 m0, s45, 0x14000
	s_add_i32 s46, s45, 0x2000
	global_load_lds_dwordx4 v132, s[14:15]
	s_add_i32 m0, s45, 0x16000
	v_mov_b32_e32 v137, 0
	global_load_lds_dwordx4 v134, s[14:15]
	s_mov_b32 m0, s45
	s_add_u32 s14, s10, 0x80000
	global_load_lds_dwordx4 v132, s[10:11]
	s_mov_b32 m0, s46
	s_addc_u32 s15, s11, 0
	s_add_i32 s47, s45, 0x4000
	global_load_lds_dwordx4 v134, s[10:11]
	s_mov_b32 m0, s47
	s_add_i32 s50, s45, 0x6000
	global_load_lds_dwordx4 v132, s[14:15]
	s_mov_b32 m0, s50
	s_mov_b32 s13, 0
	global_load_lds_dwordx4 v134, s[14:15]
	v_mov_b32_e32 v133, v137
	v_mov_b32_e32 v135, v137
	s_cmp_eq_u32 s3, 1
	s_movk_i32 s51, 0x2000
	s_mov_b32 s37, s13
	v_lshl_add_u64 v[6:7], s[0:1], 0, v[132:133]
	v_lshl_add_u64 v[4:5], s[0:1], 0, v[134:135]
	v_lshl_add_u64 v[0:1], s[10:11], 0, v[132:133]
	s_cselect_b64 s[14:15], -1, 0
	s_cmp_lg_u32 s3, 1
	v_lshl_add_u64 v[2:3], s[10:11], 0, v[134:135]
	s_cbranch_scc1 .LBB0_751
	s_barrier

.LBB0_780:
	s_waitcnt vmcnt(0)
	s_barrier
	s_mov_b64 s[0:1], exec
	v_readlane_b32 s2, v252, 1
	v_readlane_b32 s3, v252, 2
	s_and_b64 s[2:3], s[0:1], s[2:3]
	s_mov_b64 exec, s[2:3]
	s_cbranch_execz .LBB0_832
	s_add_u32 s98, s58, 0xc000
	s_addc_u32 s99, s59, 0
	s_waitcnt vmcnt(0) lgkmcnt(0)
	v_mov_b32_e32 v253, 0x26f00
	ds_read2_b32 v[254:255], v253 offset1:1
	v_readlane_b32 s100, v252, 5
	s_lshl_b32 s100, s100, 8
	s_add_u32 s100, s100, 0xc00
	v_mov_b32_e32 v253, s100
	s_waitcnt lgkmcnt(0)
	v_readfirstlane_b32 s100, v254
	v_readfirstlane_b32 s101, v255
	v_mov_b32_e32 v254, 1
	global_atomic_add v255, v253, v254, s[98:99] sc0
	s_mul_i32 s100, s100, 6
	s_mul_i32 s101, s101, 6
	s_waitcnt vmcnt(0)
	v_add_u32_e32 v255, 1, v255
	v_cmp_eq_u32_e32 vcc, s100, v255
	s_cbranch_vccz .Lpb6_notlast
	buffer_wbl2 sc1
	s_waitcnt vmcnt(0)
	v_mov_b32_e32 v253, 0x300
	global_atomic_add v255, v253, v254, s[98:99] sc0
	s_waitcnt vmcnt(0)
	v_add_u32_e32 v255, 1, v255
	v_cmp_eq_u32_e32 vcc, s101, v255
	s_cbranch_vccz .Lpb6_notlast
	v_readlane_b32 s100, v252, 26
	s_mov_b64 exec, -1
	v_mbcnt_lo_u32_b32 v253, -1, 0
	v_mbcnt_hi_u32_b32 v253, -1, v253
	v_mov_b32_e32 v254, 1
	s_mov_b32 s101, 0

.Lpb6_poll:
	global_load_dword v255, v253, s[98:99] sc1
	s_waitcnt vmcnt(0)
	v_cmp_le_u32_e32 vcc, 6, v255
	s_add_u32 s100, s100, 1
	s_cbranch_vccnz .Lpb6_done
	s_cmp_lt_u32 s100, 4096
	s_cbranch_scc0 .Lpb6_done
	s_sleep 1
	s_branch .Lpb6_poll

.Lpadskip_9:
.LBB0_832:
	s_or_b64 exec, exec, s[0:1]
	v_mov_b32_e32 v8, v182
	s_waitcnt lgkmcnt(0)
	s_barrier
	s_andn2_b64 vcc, exec, s[42:43]
	v_readfirstlane_b32 s0, v8
	s_cbranch_vccnz .LBB0_846
	v_ashrrev_i32_e32 v1, 31, v8
	v_lshrrev_b32_e32 v1, 26, v1
	v_add_u32_e32 v1, v8, v1
	v_ashrrev_i32_e32 v9, 6, v1
	v_bfe_i32 v1, v8, 27, 1
	v_lshlrev_b32_e32 v0, 4, v8
	v_lshrrev_b32_e32 v1, 22, v1
	v_add_u32_e32 v1, v0, v1
	v_and_b32_e32 v1, 0xfffffc00, v1
	v_sub_u32_e32 v1, v0, v1
	v_lshrrev_b32_e32 v2, 4, v1
	v_bitop3_b32 v2, v2, v1, 32 bitop3:0x6c
	v_ashrrev_i32_e32 v1, 31, v1
	v_lshrrev_b32_e32 v1, 26, v1
	v_add_u32_e32 v1, v2, v1
	v_ashrrev_i32_e32 v10, 6, v1
	v_mul_i32_i24_e32 v4, 64, v10
	v_sub_u32_e32 v2, v2, v4
	v_mov_b32_e32 v4, 1
	v_lshlrev_b32_e32 v3, 3, v9
	v_lshlrev_b32_e32 v1, 5, v9
	v_ashrrev_i16_sdwa v2, v4, sext(v2) dst_sel:DWORD dst_unused:UNUSED_PAD src0_sel:DWORD src1_sel:BYTE_0
	v_and_b32_e32 v3, 0xffff0, v3
	v_and_b32_e32 v1, 32, v1
	v_bfe_i32 v11, v2, 0, 16
	v_add_u32_e32 v1, v1, v11
	v_add_lshl_u32 v2, v10, v3, 12
	v_add_u32_e32 v0, 0x2000, v0
	v_lshl_add_u32 v128, v1, 1, v2
	v_ashrrev_i32_e32 v1, 31, v0
	v_lshrrev_b32_e32 v1, 22, v1
	v_add_u32_e32 v1, v0, v1
	v_ashrrev_i32_e32 v12, 10, v1
	v_mul_i32_i24_e32 v1, 0x400, v12
	v_sub_u32_e32 v0, v0, v1
	v_lshrrev_b32_e32 v1, 4, v0
	v_bitop3_b32 v0, v1, v0, 32 bitop3:0x6c
	v_ashrrev_i32_e32 v2, 31, v0
	s_add_u32 s2, s58, 0xc00000
	v_lshrrev_b32_e32 v2, 26, v2
	s_addc_u32 s33, s59, 0
	s_ashr_i32 s3, s0, 6
	v_add_u32_e32 v2, v0, v2
	s_ashr_i32 s1, s0, 8
	v_ashrrev_i32_e32 v13, 6, v2
	v_and_b32_e32 v2, 0xc0, v2
	s_lshl_b32 s34, s3, 10
	s_lshl_b32 s12, s62, 20
	s_lshl_b32 s4, s63, 20
	v_sub_u32_e32 v0, v0, v2
	s_add_u32 s4, s2, s4
	v_lshlrev_b32_e32 v1, 3, v12
	v_lshlrev_b32_e32 v3, 5, v12
	v_ashrrev_i16_sdwa v0, v4, sext(v0) dst_sel:DWORD dst_unused:UNUSED_PAD src0_sel:DWORD src1_sel:BYTE_0
	s_addc_u32 s5, s33, 0
	s_add_i32 s35, s34, 0
	v_and_b32_e32 v1, 0xffff0, v1
	v_and_b32_e32 v3, 32, v3
	v_bfe_i32 v14, v0, 0, 16
	s_add_i32 m0, s35, 0x10000
	v_add_u32_e32 v0, v3, v14
	v_add_lshl_u32 v1, v13, v1, 12
	global_load_lds_dwordx4 v128, s[4:5]
	s_add_i32 m0, s35, 0x12000
	v_lshl_add_u32 v130, v0, 1, v1
	s_add_u32 s10, s4, 0x80000
	global_load_lds_dwordx4 v130, s[4:5]
	s_addc_u32 s11, s5, 0
	s_add_i32 m0, s35, 0x14000
	v_mov_b32_e32 v133, 0
	global_load_lds_dwordx4 v128, s[10:11]
	s_add_i32 m0, s35, 0x16000
	s_add_u32 s12, s8, s12
	s_addc_u32 s13, s9, 0
	s_add_i32 s36, s35, 0x2000
	global_load_lds_dwordx4 v130, s[10:11]
	s_mov_b32 m0, s35
	s_add_u32 s10, s12, 0x80000
	global_load_lds_dwordx4 v128, s[12:13]
	s_mov_b32 m0, s36
	s_addc_u32 s11, s13, 0
	s_add_i32 s37, s35, 0x4000
	global_load_lds_dwordx4 v130, s[12:13]
	s_mov_b32 m0, s37
	s_add_i32 s38, s35, 0x6000
	global_load_lds_dwordx4 v128, s[10:11]
	s_mov_b32 m0, s38
	v_mov_b32_e32 v129, v133
	global_load_lds_dwordx4 v130, s[10:11]
	v_mov_b32_e32 v131, v133
	s_cmp_eq_u32 s1, 1
	s_mov_b32 s39, 0
	v_lshl_add_u64 v[6:7], s[4:5], 0, v[128:129]
	v_lshl_add_u64 v[4:5], s[4:5], 0, v[130:131]
	s_mov_b64 s[10:11], 0x80000
	v_lshl_add_u64 v[0:1], s[12:13], 0, v[128:129]
	s_cselect_b64 s[14:15], -1, 0
	s_cmp_lg_u32 s1, 1
	v_lshl_add_u64 v[2:3], s[12:13], 0, v[130:131]
	s_cbranch_scc1 .LBB0_835
	s_barrier

.LBB0_846:
	s_waitcnt vmcnt(0)
	s_barrier
	s_mov_b64 s[0:1], exec
	v_readlane_b32 s2, v252, 1
	v_readlane_b32 s8, v252, 10
	v_readlane_b32 s3, v252, 2
	v_readlane_b32 s9, v252, 11
	s_and_b64 s[2:3], s[0:1], s[2:3]
	s_mov_b64 s[52:53], s[8:9]
	v_readlane_b32 s10, v252, 12
	v_readlane_b32 s11, v252, 13
	v_readlane_b32 s12, v252, 14
	v_readlane_b32 s13, v252, 15
	v_readlane_b32 s14, v252, 16
	v_readlane_b32 s15, v252, 17
	v_readlane_b32 s16, v252, 18
	v_readlane_b32 s17, v252, 19
	v_readlane_b32 s18, v252, 20
	v_readlane_b32 s19, v252, 21
	v_readlane_b32 s20, v252, 22
	v_readlane_b32 s21, v252, 23
	v_readlane_b32 s22, v252, 24
	v_readlane_b32 s23, v252, 25
	s_mov_b64 exec, s[2:3]
	s_cbranch_execz .LBB0_898
	s_add_u32 s98, s58, 0xc000
	s_addc_u32 s99, s59, 0
	s_waitcnt vmcnt(0) lgkmcnt(0)
	v_mov_b32_e32 v253, 0x26f00
	ds_read2_b32 v[254:255], v253 offset1:1
	v_readlane_b32 s100, v252, 5
	s_lshl_b32 s100, s100, 8
	s_add_u32 s100, s100, 0xc00
	v_mov_b32_e32 v253, s100
	s_waitcnt lgkmcnt(0)
	v_readfirstlane_b32 s100, v254
	v_readfirstlane_b32 s101, v255
	v_mov_b32_e32 v254, 1
	global_atomic_add v255, v253, v254, s[98:99] sc0
	s_mul_i32 s100, s100, 7
	s_mul_i32 s101, s101, 7
	s_waitcnt vmcnt(0)
	v_add_u32_e32 v255, 1, v255
	v_cmp_eq_u32_e32 vcc, s100, v255
	s_cbranch_vccz .Lpb7_notlast
	buffer_wbl2 sc1
	s_waitcnt vmcnt(0)
	v_mov_b32_e32 v253, 0x300
	global_atomic_add v255, v253, v254, s[98:99] sc0
	s_waitcnt vmcnt(0)
	v_add_u32_e32 v255, 1, v255
	v_cmp_eq_u32_e32 vcc, s101, v255
	s_cbranch_vccz .Lpb7_notlast
	v_readlane_b32 s100, v252, 26
	s_mov_b64 exec, -1
	v_mbcnt_lo_u32_b32 v253, -1, 0
	v_mbcnt_hi_u32_b32 v253, -1, v253
	v_mov_b32_e32 v254, 1
	s_mov_b32 s101, 0

.Lpb7_poll:
	global_load_dword v255, v253, s[98:99] sc1
	s_waitcnt vmcnt(0)
	v_cmp_le_u32_e32 vcc, 7, v255
	s_add_u32 s100, s100, 1
	s_cbranch_vccnz .Lpb7_done
	s_cmp_lt_u32 s100, 4096
	s_cbranch_scc0 .Lpb7_done
	s_sleep 1
	s_branch .Lpb7_poll

.Lpadskip_10:
.LBB0_898:
	s_or_b64 exec, exec, s[0:1]
	s_waitcnt lgkmcnt(0)
	v_mov_b32_e32 v0, v182
	s_barrier
	v_readlane_b32 s0, v252, 0
	v_ashrrev_i32_e32 v0, 5, v0
	v_and_b32_e32 v0, -2, v0
	v_lshl_add_u32 v16, s0, 4, v0
	s_movk_i32 s0, 0x4000
	v_cmp_gt_i32_e32 vcc, s0, v16
	s_and_saveexec_b64 s[0:1], vcc
	s_cbranch_execz .LBB0_901
	v_lshlrev_b32_e32 v0, 2, v182
	v_and_b32_e32 v18, 0xfc, v0
	v_mov_b32_e32 v1, 0
	v_lshlrev_b32_e32 v0, 2, v18
	v_lshl_add_u64 v[20:21], s[54:55], 0, v[0:1]
	s_mov_b64 s[0:1], 0x1000
	v_lshl_add_u64 v[22:23], v[20:21], 0, s[0:1]
	s_mov_b64 s[0:1], 0x1400
	v_lshl_add_u64 v[24:25], v[20:21], 0, s[0:1]
	s_mov_b64 s[0:1], 0x1800
	v_lshl_add_u64 v[26:27], v[20:21], 0, s[0:1]
	s_mov_b64 s[0:1], 0x1c00
	s_lshl_b32 s5, s96, 4
	v_lshl_add_u64 v[28:29], v[20:21], 0, s[0:1]
	s_mov_b64 s[2:3], 0
	s_movk_i32 s8, 0x2000
	s_movk_i32 s9, 0x1000
	s_movk_i32 s10, 0x3000
	s_mov_b32 s4, 0x3a000000
	s_mov_b32 s11, 0x800000
	s_movk_i32 s12, 0x3fff
	v_mov_b32_e32 v30, 0x358637bd
	global_load_dwordx4 v[140:143], v[20:21], off
	global_load_dwordx4 v[144:147], v[20:21], off offset:1024
	global_load_dwordx4 v[148:151], v[20:21], off offset:2048
	global_load_dwordx4 v[152:155], v[20:21], off offset:3072
	global_load_dwordx4 v[156:159], v[22:23], off
	global_load_dwordx4 v[160:163], v[24:25], off
	global_load_dwordx4 v[164:167], v[26:27], off
	global_load_dwordx4 v[168:171], v[28:29], off
	s_waitcnt vmcnt(0)

	.amdhsa_kernel _Z4mega6Params
		.amdhsa_group_segment_fixed_size 0
		.amdhsa_private_segment_fixed_size 0
		.amdhsa_kernarg_size 384
		.amdhsa_user_sgpr_count 2
		.amdhsa_user_sgpr_dispatch_ptr 0
		.amdhsa_user_sgpr_queue_ptr 0
		.amdhsa_user_sgpr_kernarg_segment_ptr 1
		.amdhsa_user_sgpr_dispatch_id 0
		.amdhsa_user_sgpr_kernarg_preload_length 0
		.amdhsa_user_sgpr_kernarg_preload_offset 0
		.amdhsa_user_sgpr_private_segment_size 0
		.amdhsa_uses_dynamic_stack 0
		.amdhsa_enable_private_segment 0
		.amdhsa_system_sgpr_workgroup_id_x 1
		.amdhsa_system_sgpr_workgroup_id_y 0
		.amdhsa_system_sgpr_workgroup_id_z 0
		.amdhsa_system_sgpr_workgroup_info 0
		.amdhsa_system_vgpr_workitem_id 2
		.amdhsa_next_free_vgpr 256
		.amdhsa_next_free_sgpr 102
		.amdhsa_accum_offset 256
		.amdhsa_reserve_vcc 1
		.amdhsa_float_round_mode_32 0
		.amdhsa_float_round_mode_16_64 0
		.amdhsa_float_denorm_mode_32 3
		.amdhsa_float_denorm_mode_16_64 3
		.amdhsa_dx10_clamp 1
		.amdhsa_ieee_mode 1
		.amdhsa_fp16_overflow 0
		.amdhsa_tg_split 0
		.amdhsa_exception_fp_ieee_invalid_op 0
		.amdhsa_exception_fp_denorm_src 0
		.amdhsa_exception_fp_ieee_div_zero 0
		.amdhsa_exception_fp_ieee_overflow 0
		.amdhsa_exception_fp_ieee_underflow 0
		.amdhsa_exception_fp_ieee_inexact 0
		.amdhsa_exception_int_div_zero 0
	.end_amdhsa_kernel

amdhsa.kernels:
  - .agpr_count:     0
    .args:
      - .offset:         0
        .size:           128
        .value_kind:     by_value
      - .offset:         128
        .size:           4
        .value_kind:     hidden_block_count_x
      - .offset:         132
        .size:           4
        .value_kind:     hidden_block_count_y
      - .offset:         136
        .size:           4
        .value_kind:     hidden_block_count_z
      - .offset:         140
        .size:           2
        .value_kind:     hidden_group_size_x
      - .offset:         142
        .size:           2
        .value_kind:     hidden_group_size_y
      - .offset:         144
        .size:           2
        .value_kind:     hidden_group_size_z
      - .offset:         146
        .size:           2
        .value_kind:     hidden_remainder_x
      - .offset:         148
        .size:           2
        .value_kind:     hidden_remainder_y
      - .offset:         150
        .size:           2
        .value_kind:     hidden_remainder_z
      - .offset:         168
        .size:           8
        .value_kind:     hidden_global_offset_x
      - .offset:         176
        .size:           8
        .value_kind:     hidden_global_offset_y
      - .offset:         184
        .size:           8
        .value_kind:     hidden_global_offset_z
      - .offset:         192
        .size:           2
        .value_kind:     hidden_grid_dims
      - .offset:         216
        .size:           8
        .value_kind:     hidden_multigrid_sync_arg
      - .offset:         248
        .size:           4
        .value_kind:     hidden_dynamic_lds_size
    .group_segment_fixed_size: 0
    .kernarg_segment_align: 8
    .kernarg_segment_size: 384
    .language:       OpenCL C
    .language_version:
      - 2
      - 0
    .max_flat_workgroup_size: 512
    .name:           _Z4mega6Params
    .private_segment_fixed_size: 0
    .sgpr_count:     108
    .sgpr_spill_count: 43
    .symbol:         _Z4mega6Params.kd
    .uniform_work_group_size: 1
    .uses_dynamic_stack: false
    .vgpr_count:     256
    .vgpr_spill_count: 0
    .wavefront_size: 64
